# v26 plus one in-loop copy slot per down-projection K-iteration for 3/4 of the copy units still left in the attention phase (as in v18)
# speedup vs baseline: 1.0198x; 1.0198x over previous
.LBB0_1735:
	ds_read_b128 v[162:165], v159
	ds_read_b128 v[166:169], v159 offset:1024
	ds_read_b128 v[170:173], v159 offset:2048
	ds_read_b128 v[174:177], v159 offset:3072
	ds_read_b128 v[178:181], v160
	ds_read_b128 v[182:185], v160 offset:1024
	ds_read_b128 v[186:189], v160 offset:2048
	ds_read_b128 v[190:193], v160 offset:3072
	s_add_i32 s68, s56, 2
	s_add_u32 s54, s52, 0x100
	s_addc_u32 s55, s53, 0
	s_cmp_eq_u32 s34, s56
	s_cselect_b32 s56, s48, s37
	s_cselect_b32 s59, s39, s55
	s_cselect_b32 s58, s38, s54
	s_cselect_b32 s57, s49, s42
	v_lshl_add_u64 v[146:147], s[52:53], 0, v[142:143]
	s_add_i32 m0, s18, 0xc000
	ds_read_b128 v[194:197], v161
	ds_read_b128 v[198:201], v161 offset:1024
	ds_read_b128 v[202:205], v161 offset:2048
	ds_read_b128 v[206:209], v161 offset:3072
	ds_read_b128 v[210:213], v161 offset:4096
	ds_read_b128 v[214:217], v161 offset:5120
	ds_read_b128 v[218:221], v161 offset:6144
	ds_read_b128 v[222:225], v161 offset:7168
	global_load_lds_dwordx4 v[146:147], off
	v_lshl_add_u64 v[146:147], s[52:53], 0, v[144:145]
	s_add_i32 m0, s18, 0xe000
	s_nop 0
	global_load_lds_dwordx4 v[146:147], off
	s_waitcnt vmcnt(9)
	s_waitcnt lgkmcnt(0)
	s_barrier
	s_setprio 1
	v_mfma_f32_16x16x32_bf16 v[124:127], v[162:165], v[194:197], v[124:127]
	v_mfma_f32_16x16x32_bf16 v[120:123], v[170:173], v[194:197], v[120:123]
	v_mfma_f32_16x16x32_bf16 v[108:111], v[162:165], v[202:205], v[108:111]
	v_mfma_f32_16x16x32_bf16 v[104:107], v[170:173], v[202:205], v[104:107]
	v_mfma_f32_16x16x32_bf16 v[92:95], v[162:165], v[210:213], v[92:95]
	v_mfma_f32_16x16x32_bf16 v[88:91], v[170:173], v[210:213], v[88:91]
	v_mfma_f32_16x16x32_bf16 v[76:79], v[162:165], v[218:221], v[76:79]
	v_mfma_f32_16x16x32_bf16 v[72:75], v[170:173], v[218:221], v[72:75]
	v_mfma_f32_16x16x32_bf16 v[124:127], v[166:169], v[198:201], v[124:127]
	v_mfma_f32_16x16x32_bf16 v[120:123], v[174:177], v[198:201], v[120:123]
	v_mfma_f32_16x16x32_bf16 v[108:111], v[166:169], v[206:209], v[108:111]
	v_mfma_f32_16x16x32_bf16 v[104:107], v[174:177], v[206:209], v[104:107]
	v_mfma_f32_16x16x32_bf16 v[92:95], v[166:169], v[214:217], v[92:95]
	v_mfma_f32_16x16x32_bf16 v[88:91], v[174:177], v[214:217], v[88:91]
	v_mfma_f32_16x16x32_bf16 v[76:79], v[166:169], v[222:225], v[76:79]
	v_mfma_f32_16x16x32_bf16 v[72:75], v[174:177], v[222:225], v[72:75]
	v_mfma_f32_16x16x32_bf16 v[116:119], v[178:181], v[194:197], v[116:119]
	v_mfma_f32_16x16x32_bf16 v[112:115], v[186:189], v[194:197], v[112:115]
	v_mfma_f32_16x16x32_bf16 v[100:103], v[178:181], v[202:205], v[100:103]
	v_mfma_f32_16x16x32_bf16 v[96:99], v[186:189], v[202:205], v[96:99]
	v_mfma_f32_16x16x32_bf16 v[84:87], v[178:181], v[210:213], v[84:87]
	v_mfma_f32_16x16x32_bf16 v[80:83], v[186:189], v[210:213], v[80:83]
	v_mfma_f32_16x16x32_bf16 v[68:71], v[178:181], v[218:221], v[68:71]
	v_mfma_f32_16x16x32_bf16 v[64:67], v[186:189], v[218:221], v[64:67]
	v_mfma_f32_16x16x32_bf16 v[116:119], v[182:185], v[198:201], v[116:119]
	v_mfma_f32_16x16x32_bf16 v[112:115], v[190:193], v[198:201], v[112:115]
	v_mfma_f32_16x16x32_bf16 v[100:103], v[182:185], v[206:209], v[100:103]
	v_mfma_f32_16x16x32_bf16 v[96:99], v[190:193], v[206:209], v[96:99]
	v_mfma_f32_16x16x32_bf16 v[84:87], v[182:185], v[214:217], v[84:87]
	v_mfma_f32_16x16x32_bf16 v[80:83], v[190:193], v[214:217], v[80:83]
	v_mfma_f32_16x16x32_bf16 v[68:71], v[182:185], v[222:225], v[68:71]
	v_mfma_f32_16x16x32_bf16 v[64:67], v[190:193], v[222:225], v[64:67]
	s_setprio 0
	s_barrier
	s_add_i32 s52, s63, s15
	v_lshl_add_u64 v[146:147], s[56:57], 0, v[132:133]
	s_mov_b32 m0, s52
	ds_read_b128 v[194:197], v161 offset:16384
	ds_read_b128 v[198:201], v161 offset:17408
	ds_read_b128 v[202:205], v161 offset:18432
	ds_read_b128 v[206:209], v161 offset:19456
	ds_read_b128 v[210:213], v161 offset:20480
	ds_read_b128 v[214:217], v161 offset:21504
	ds_read_b128 v[218:221], v161 offset:22528
	ds_read_b128 v[222:225], v161 offset:23552
	global_load_lds_dwordx4 v[146:147], off
	s_add_i32 m0, s52, 0x2000
	s_add_u32 s52, s56, 0xb0000
	v_lshl_add_u64 v[226:227], s[56:57], 0, v[136:137]
	s_addc_u32 s53, s57, 0
	s_add_i32 s69, s64, s15
	global_load_lds_dwordx4 v[226:227], off
	v_lshl_add_u64 v[228:229], s[52:53], 0, v[132:133]
	s_mov_b32 m0, s69
	v_lshl_add_u64 v[230:231], s[58:59], 0, v[134:135]
	global_load_lds_dwordx4 v[228:229], off
	v_lshl_add_u64 v[228:229], s[52:53], 0, v[136:137]
	s_add_i32 m0, s69, 0x2000
	s_nop 0
	global_load_lds_dwordx4 v[228:229], off
	v_lshl_add_u64 v[228:229], s[58:59], 0, v[130:131]
	s_mov_b32 m0, s18
	s_nop 0
	global_load_lds_dwordx4 v[228:229], off
	s_mov_b32 m0, s19
	s_nop 0
	global_load_lds_dwordx4 v[230:231], off
	s_waitcnt vmcnt(8)
	s_waitcnt lgkmcnt(0)
	s_barrier
	s_setprio 1
	v_mfma_f32_16x16x32_bf16 v[60:63], v[162:165], v[194:197], v[60:63]
	v_mfma_f32_16x16x32_bf16 v[56:59], v[170:173], v[194:197], v[56:59]
	v_mfma_f32_16x16x32_bf16 v[44:47], v[162:165], v[202:205], v[44:47]
	v_mfma_f32_16x16x32_bf16 v[40:43], v[170:173], v[202:205], v[40:43]
	v_mfma_f32_16x16x32_bf16 v[28:31], v[162:165], v[210:213], v[28:31]
	v_mfma_f32_16x16x32_bf16 v[24:27], v[170:173], v[210:213], v[24:27]
	v_mfma_f32_16x16x32_bf16 v[12:15], v[162:165], v[218:221], v[12:15]
	v_mfma_f32_16x16x32_bf16 v[8:11], v[170:173], v[218:221], v[8:11]
	v_mfma_f32_16x16x32_bf16 v[60:63], v[166:169], v[198:201], v[60:63]
	v_mfma_f32_16x16x32_bf16 v[56:59], v[174:177], v[198:201], v[56:59]
	v_mfma_f32_16x16x32_bf16 v[44:47], v[166:169], v[206:209], v[44:47]
	v_mfma_f32_16x16x32_bf16 v[40:43], v[174:177], v[206:209], v[40:43]
	v_mfma_f32_16x16x32_bf16 v[28:31], v[166:169], v[214:217], v[28:31]
	v_mfma_f32_16x16x32_bf16 v[24:27], v[174:177], v[214:217], v[24:27]
	v_mfma_f32_16x16x32_bf16 v[12:15], v[166:169], v[222:225], v[12:15]
	v_mfma_f32_16x16x32_bf16 v[8:11], v[174:177], v[222:225], v[8:11]
	v_mfma_f32_16x16x32_bf16 v[52:55], v[178:181], v[194:197], v[52:55]
	v_mfma_f32_16x16x32_bf16 v[48:51], v[186:189], v[194:197], v[48:51]
	v_mfma_f32_16x16x32_bf16 v[36:39], v[178:181], v[202:205], v[36:39]
	v_mfma_f32_16x16x32_bf16 v[32:35], v[186:189], v[202:205], v[32:35]
	v_mfma_f32_16x16x32_bf16 v[20:23], v[178:181], v[210:213], v[20:23]
	v_mfma_f32_16x16x32_bf16 v[16:19], v[186:189], v[210:213], v[16:19]
	v_mfma_f32_16x16x32_bf16 v[4:7], v[178:181], v[218:221], v[4:7]
	v_mfma_f32_16x16x32_bf16 v[0:3], v[186:189], v[218:221], v[0:3]
	v_mfma_f32_16x16x32_bf16 v[52:55], v[182:185], v[198:201], v[52:55]
	v_mfma_f32_16x16x32_bf16 v[48:51], v[190:193], v[198:201], v[48:51]
	v_mfma_f32_16x16x32_bf16 v[36:39], v[182:185], v[206:209], v[36:39]
	v_mfma_f32_16x16x32_bf16 v[32:35], v[190:193], v[206:209], v[32:35]
	v_mfma_f32_16x16x32_bf16 v[20:23], v[182:185], v[214:217], v[20:23]
	v_mfma_f32_16x16x32_bf16 v[16:19], v[190:193], v[214:217], v[16:19]
	v_mfma_f32_16x16x32_bf16 v[4:7], v[182:185], v[222:225], v[4:7]
	v_mfma_f32_16x16x32_bf16 v[0:3], v[190:193], v[222:225], v[0:3]
	s_setprio 0
	s_barrier
	buffer_store_dwordx4 v[234:237], v238, s[72:75], s101 offen nt
	s_add_i32 s69, 0, 0x18000
	v_add_u32_e32 v138, s69, v141
	s_add_i32 s70, 0, 0x1c000
	ds_read_b128 v[162:165], v138
	ds_read_b128 v[166:169], v138 offset:1024
	ds_read_b128 v[170:173], v138 offset:2048
	ds_read_b128 v[174:177], v138 offset:3072
	v_add_u32_e32 v138, s70, v141
	ds_read_b128 v[178:181], v138
	ds_read_b128 v[182:185], v138 offset:1024
	ds_read_b128 v[186:189], v138 offset:2048
	ds_read_b128 v[190:193], v138 offset:3072
	s_add_u32 s52, s58, 0xb0000
	s_addc_u32 s53, s59, 0
	s_mov_b32 m0, s35
	v_lshl_add_u64 v[232:233], s[52:53], 0, v[130:131]
	ds_read_b128 v[194:197], v161 offset:32768
	ds_read_b128 v[198:201], v161 offset:33792
	ds_read_b128 v[202:205], v161 offset:34816
	ds_read_b128 v[206:209], v161 offset:35840
	ds_read_b128 v[210:213], v161 offset:36864
	ds_read_b128 v[214:217], v161 offset:37888
	ds_read_b128 v[218:221], v161 offset:38912
	ds_read_b128 v[222:225], v161 offset:39936
	global_load_lds_dwordx4 v[232:233], off
	v_lshl_add_u64 v[232:233], s[52:53], 0, v[134:135]
	s_mov_b32 m0, s43
	s_nop 0
	global_load_lds_dwordx4 v[232:233], off
	buffer_load_dwordx4 v[234:237], v238, s[96:99], s100 offen nt
	s_waitcnt vmcnt(10)
	s_waitcnt lgkmcnt(0)
	s_barrier
	s_setprio 1
	v_mfma_f32_16x16x32_bf16 v[124:127], v[162:165], v[194:197], v[124:127]
	v_mfma_f32_16x16x32_bf16 v[120:123], v[170:173], v[194:197], v[120:123]
	v_mfma_f32_16x16x32_bf16 v[108:111], v[162:165], v[202:205], v[108:111]
	v_mfma_f32_16x16x32_bf16 v[104:107], v[170:173], v[202:205], v[104:107]
	v_mfma_f32_16x16x32_bf16 v[92:95], v[162:165], v[210:213], v[92:95]
	v_mfma_f32_16x16x32_bf16 v[88:91], v[170:173], v[210:213], v[88:91]
	v_mfma_f32_16x16x32_bf16 v[76:79], v[162:165], v[218:221], v[76:79]
	v_mfma_f32_16x16x32_bf16 v[72:75], v[170:173], v[218:221], v[72:75]
	v_mfma_f32_16x16x32_bf16 v[124:127], v[166:169], v[198:201], v[124:127]
	v_mfma_f32_16x16x32_bf16 v[120:123], v[174:177], v[198:201], v[120:123]
	v_mfma_f32_16x16x32_bf16 v[108:111], v[166:169], v[206:209], v[108:111]
	v_mfma_f32_16x16x32_bf16 v[104:107], v[174:177], v[206:209], v[104:107]
	v_mfma_f32_16x16x32_bf16 v[92:95], v[166:169], v[214:217], v[92:95]
	v_mfma_f32_16x16x32_bf16 v[88:91], v[174:177], v[214:217], v[88:91]
	v_mfma_f32_16x16x32_bf16 v[76:79], v[166:169], v[222:225], v[76:79]
	v_mfma_f32_16x16x32_bf16 v[72:75], v[174:177], v[222:225], v[72:75]
	v_mfma_f32_16x16x32_bf16 v[116:119], v[178:181], v[194:197], v[116:119]
	v_mfma_f32_16x16x32_bf16 v[112:115], v[186:189], v[194:197], v[112:115]
	v_mfma_f32_16x16x32_bf16 v[100:103], v[178:181], v[202:205], v[100:103]
	v_mfma_f32_16x16x32_bf16 v[96:99], v[186:189], v[202:205], v[96:99]
	v_mfma_f32_16x16x32_bf16 v[84:87], v[178:181], v[210:213], v[84:87]
	v_mfma_f32_16x16x32_bf16 v[80:83], v[186:189], v[210:213], v[80:83]
	v_mfma_f32_16x16x32_bf16 v[68:71], v[178:181], v[218:221], v[68:71]
	v_mfma_f32_16x16x32_bf16 v[64:67], v[186:189], v[218:221], v[64:67]
	v_mfma_f32_16x16x32_bf16 v[116:119], v[182:185], v[198:201], v[116:119]
	v_mfma_f32_16x16x32_bf16 v[112:115], v[190:193], v[198:201], v[112:115]
	v_mfma_f32_16x16x32_bf16 v[100:103], v[182:185], v[206:209], v[100:103]
	v_mfma_f32_16x16x32_bf16 v[96:99], v[190:193], v[206:209], v[96:99]
	v_mfma_f32_16x16x32_bf16 v[84:87], v[182:185], v[214:217], v[84:87]
	v_mfma_f32_16x16x32_bf16 v[80:83], v[190:193], v[214:217], v[80:83]
	v_mfma_f32_16x16x32_bf16 v[68:71], v[182:185], v[222:225], v[68:71]
	v_mfma_f32_16x16x32_bf16 v[64:67], v[190:193], v[222:225], v[64:67]
	s_setprio 0
	s_barrier
	s_add_i32 s52, s69, s15
	v_lshl_add_u64 v[146:147], v[146:147], 0, s[22:23]
	s_mov_b32 m0, s52
	ds_read_b128 v[194:197], v161 offset:49152
	ds_read_b128 v[198:201], v161 offset:50176
	ds_read_b128 v[202:205], v161 offset:51200
	ds_read_b128 v[206:209], v161 offset:52224
	ds_read_b128 v[210:213], v161 offset:53248
	ds_read_b128 v[214:217], v161 offset:54272
	ds_read_b128 v[218:221], v161 offset:55296
	ds_read_b128 v[222:225], v161 offset:56320
	global_load_lds_dwordx4 v[146:147], off
	s_add_i32 m0, s52, 0x2000
	s_add_u32 s52, s56, 0xb0080
	v_lshl_add_u64 v[146:147], v[226:227], 0, s[22:23]
	s_addc_u32 s53, s57, 0
	s_add_i32 s56, s70, s15
	global_load_lds_dwordx4 v[146:147], off
	v_lshl_add_u64 v[146:147], s[52:53], 0, v[132:133]
	s_mov_b32 m0, s56
	s_nop 0
	global_load_lds_dwordx4 v[146:147], off
	v_lshl_add_u64 v[146:147], s[52:53], 0, v[136:137]
	s_add_i32 m0, s56, 0x2000
	s_nop 0
	global_load_lds_dwordx4 v[146:147], off
	v_lshl_add_u64 v[146:147], v[228:229], 0, s[22:23]
	s_mov_b32 m0, s46
	s_nop 0
	global_load_lds_dwordx4 v[146:147], off
	v_lshl_add_u64 v[146:147], v[230:231], 0, s[22:23]
	s_mov_b32 m0, s47
	s_nop 0
	global_load_lds_dwordx4 v[146:147], off
	s_waitcnt vmcnt(10)
	s_waitcnt lgkmcnt(0)
	s_barrier
	s_setprio 1
	v_mfma_f32_16x16x32_bf16 v[60:63], v[162:165], v[194:197], v[60:63]
	v_mfma_f32_16x16x32_bf16 v[56:59], v[170:173], v[194:197], v[56:59]
	v_mfma_f32_16x16x32_bf16 v[44:47], v[162:165], v[202:205], v[44:47]
	v_mfma_f32_16x16x32_bf16 v[40:43], v[170:173], v[202:205], v[40:43]
	v_mfma_f32_16x16x32_bf16 v[28:31], v[162:165], v[210:213], v[28:31]
	v_mfma_f32_16x16x32_bf16 v[24:27], v[170:173], v[210:213], v[24:27]
	v_mfma_f32_16x16x32_bf16 v[12:15], v[162:165], v[218:221], v[12:15]
	v_mfma_f32_16x16x32_bf16 v[8:11], v[170:173], v[218:221], v[8:11]
	v_mfma_f32_16x16x32_bf16 v[60:63], v[166:169], v[198:201], v[60:63]
	v_mfma_f32_16x16x32_bf16 v[56:59], v[174:177], v[198:201], v[56:59]
	v_mfma_f32_16x16x32_bf16 v[44:47], v[166:169], v[206:209], v[44:47]
	v_mfma_f32_16x16x32_bf16 v[40:43], v[174:177], v[206:209], v[40:43]
	v_mfma_f32_16x16x32_bf16 v[28:31], v[166:169], v[214:217], v[28:31]
	v_mfma_f32_16x16x32_bf16 v[24:27], v[174:177], v[214:217], v[24:27]
	v_mfma_f32_16x16x32_bf16 v[12:15], v[166:169], v[222:225], v[12:15]
	v_mfma_f32_16x16x32_bf16 v[8:11], v[174:177], v[222:225], v[8:11]
	v_mfma_f32_16x16x32_bf16 v[52:55], v[178:181], v[194:197], v[52:55]
	v_mfma_f32_16x16x32_bf16 v[48:51], v[186:189], v[194:197], v[48:51]
	v_mfma_f32_16x16x32_bf16 v[36:39], v[178:181], v[202:205], v[36:39]
	v_mfma_f32_16x16x32_bf16 v[32:35], v[186:189], v[202:205], v[32:35]
	v_mfma_f32_16x16x32_bf16 v[20:23], v[178:181], v[210:213], v[20:23]
	v_mfma_f32_16x16x32_bf16 v[16:19], v[186:189], v[210:213], v[16:19]
	v_mfma_f32_16x16x32_bf16 v[4:7], v[178:181], v[218:221], v[4:7]
	v_mfma_f32_16x16x32_bf16 v[0:3], v[186:189], v[218:221], v[0:3]
	v_mfma_f32_16x16x32_bf16 v[52:55], v[182:185], v[198:201], v[52:55]
	v_mfma_f32_16x16x32_bf16 v[48:51], v[190:193], v[198:201], v[48:51]
	v_mfma_f32_16x16x32_bf16 v[36:39], v[182:185], v[206:209], v[36:39]
	v_mfma_f32_16x16x32_bf16 v[32:35], v[190:193], v[206:209], v[32:35]
	v_mfma_f32_16x16x32_bf16 v[20:23], v[182:185], v[214:217], v[20:23]
	v_mfma_f32_16x16x32_bf16 v[16:19], v[190:193], v[214:217], v[16:19]
	v_mfma_f32_16x16x32_bf16 v[4:7], v[182:185], v[222:225], v[4:7]
	v_mfma_f32_16x16x32_bf16 v[0:3], v[190:193], v[222:225], v[0:3]
	s_sub_u32 s76, s76, 1
	s_cmp_eq_u32 s76, 0
	s_cselect_b32 s100, 0x70000000, s100
	s_mov_b32 s101, s100
	s_add_i32 s32, s32, 1
	s_cmp_eq_u32 s32, 12
	s_cselect_b32 vcc_lo, 0x3000, 0
	s_cselect_b32 s32, 0, s32
	s_add_u32 s100, s100, vcc_lo
	s_addk_i32 s100, 0x400
	s_add_u32 s37, s37, 0x100
	s_addc_u32 s42, s42, 0
	s_cmp_ge_u32 s68, s33
	s_mov_b64 s[52:53], s[54:55]
	s_mov_b32 s56, s68
	s_setprio 0
	s_barrier
	s_cbranch_scc0 .LBB0_1735
	s_xor_b64 s[50:51], s[50:51], -1
	s_and_b64 vcc, exec, s[24:25]
	s_cbranch_vccz .LBB0_1757
